# FFN norm row remap: each wave takes 16 consecutive sequence rows (one batch -> adaLN vectors L1-resident) then its context rows (on keep_v8)
# baseline (speedup 1.0000x reference)
.LBB0_775:
	s_xor_b64 s[72:73], s[18:19], -1
	s_cmp_lg_u32 s65, 3
	s_cselect_b64 s[16:17], -1, 0
	s_cmp_eq_u32 s65, 3
	s_cselect_b64 s[94:95], -1, 0
	s_and_b64 s[26:27], s[94:95], exec
	s_mov_b32 s20, 0x9000
	s_cselect_b32 s20, 0x8000, s20
	s_ashr_i32 s24, s24, 6
	v_readlane_b32 s25, v255, 1
	s_add_i32 s24, s24, s25
	s_cmpk_lg_u32 s10, 0x800
	s_cbranch_scc1 .Lnm_noshift
	s_lshl_b32 s24, s24, 4
.Lnm_noshift:
	s_cmp_ge_i32 s24, s20
	s_cbranch_scc1 .LBB0_784
	v_readlane_b32 s26, v255, 57
	s_add_u32 s36, s6, 0x19000000
	v_readlane_b32 s27, v255, 58
	s_addc_u32 s37, s7, 0
	s_lshl_b64 s[26:27], s[26:27], 2
	s_add_u32 s25, s6, s26
	s_addc_u32 s29, s7, s27
	s_cmp_lt_u32 s9, 2
	s_cselect_b64 s[6:7], -1, 0
	s_and_b64 s[26:27], s[6:7], exec
	v_readlane_b32 s28, v255, 56
	s_cselect_b32 s9, s37, 0
	s_cselect_b32 s26, s36, 0
	s_lshl_b32 s27, s28, 13
	v_lshlrev_b32_e32 v18, 2, v0
	s_waitcnt lgkmcnt(0)
	s_add_u32 s2, s2, s27
	v_and_b32_e32 v34, 0xfc, v18
	s_addc_u32 s3, s3, 0
	v_lshlrev_b32_e32 v14, 2, v34
	global_load_dwordx4 v[2:5], v14, s[2:3]
	global_load_dwordx4 v[6:9], v14, s[2:3] offset:1024
	global_load_dwordx4 v[10:13], v14, s[2:3] offset:2048
	s_nop 0
	global_load_dwordx4 v[14:17], v14, s[2:3] offset:3072
	s_mul_i32 s2, s28, 0x6000
	s_add_u32 s28, s25, s2
	s_addc_u32 s29, s29, 0
	s_add_u32 s38, s26, 0x800000
	s_addc_u32 s39, s9, 0
	s_add_u32 s60, s26, 0x1000000
	s_addc_u32 s61, s9, 0
	s_add_u32 s74, s26, 0x1800000
	s_addc_u32 s75, s9, 0
	s_movk_i32 s2, 0x80
	s_ashr_i32 s25, s24, 31
	v_bitop3_b32 v52, v18, s2, v246 bitop3:0x6c
	s_lshl_b64 s[2:3], s[24:25], 11
	v_and_b32_e32 v0, 63, v0
	s_add_u32 s2, s4, s2
	v_bitop3_b32 v35, v18, 4, v246 bitop3:0x6c
	v_bitop3_b32 v48, v18, 8, v246 bitop3:0x6c
	v_bitop3_b32 v49, v18, 16, v246 bitop3:0x6c
	v_bitop3_b32 v50, v18, 32, v246 bitop3:0x6c
	v_bitop3_b32 v51, v18, 64, v246 bitop3:0x6c
	v_or_b32_e32 v18, 0x100, v34
	v_or_b32_e32 v20, 0x200, v34
	v_or_b32_e32 v22, 0x300, v34
	v_lshlrev_b32_e32 v0, 3, v0
	s_addc_u32 s3, s5, s3
	v_lshl_add_u64 v[36:37], s[2:3], 0, v[0:1]
	v_lshlrev_b32_e32 v53, 2, v18
	v_lshlrev_b32_e32 v54, 2, v20
	v_lshlrev_b32_e32 v55, 2, v22
	s_branch .LBB0_778
.LBB0_777:
	s_waitcnt vmcnt(3)
	v_pk_mul_f32 v[42:43], v[32:33], v[32:33]
	v_pk_mul_f32 v[44:45], v[30:31], v[30:31]
	s_waitcnt vmcnt(2)
	v_pk_mul_f32 v[38:39], v[28:29], v[28:29]
	v_pk_mul_f32 v[40:41], v[26:27], v[26:27]
	v_pk_mov_b32 v[46:47], v[44:45], v[42:43] op_sel:[1,0]
	v_mov_b32_e32 v45, v43
	v_pk_add_f32 v[42:43], v[46:47], v[44:45]
	v_pk_mov_b32 v[44:45], v[40:41], v[38:39] op_sel:[1,0]
	v_mov_b32_e32 v41, v39
	s_waitcnt vmcnt(1)
	v_mul_f32_e32 v0, v22, v22
	v_pk_add_f32 v[38:39], v[44:45], v[40:41]
	v_pk_fma_f32 v[40:41], v[22:23], v[22:23], v[0:1] op_sel_hi:[1,1,0]
	v_mul_f32_e32 v0, v24, v24
	v_pk_add_f32 v[42:43], v[42:43], v[42:43] op_sel_hi:[0,1]
	v_pk_add_f32 v[38:39], v[38:39], v[38:39] op_sel_hi:[0,1]
	v_pk_fma_f32 v[44:45], v[24:25], v[24:25], v[0:1] op_sel_hi:[1,1,0]
	s_waitcnt vmcnt(0)
	v_mul_f32_e32 v40, v18, v18
	v_mul_f32_e32 v44, v19, v19
	v_mul_f32_e32 v42, v20, v20
	v_mul_f32_e32 v38, v21, v21
	v_pk_add_f32 v[40:41], v[40:41], v[44:45]
	v_pk_add_f32 v[38:39], v[42:43], v[38:39]
	s_min_i32 s2, s24, 0x8000
	v_pk_add_f32 v[38:39], v[40:41], v[38:39]
	s_ashr_i32 s2, s2, 11
	v_add_f32_e32 v0, v38, v39
	ds_bpermute_b32 v38, v35, v0
	s_mul_hi_i32 s3, s2, 0x9000
	s_mul_i32 s2, s2, 0x9000
	s_add_u32 s4, s28, s2
	s_addc_u32 s5, s29, s3
	s_waitcnt lgkmcnt(0)
	v_add_f32_e32 v0, v0, v38
	ds_bpermute_b32 v38, v48, v0
	s_add_u32 s96, s4, 0x1000
	s_addc_u32 s97, s5, 0
	v_lshlrev_b32_e32 v46, 2, v34
	s_mov_b32 s98, s24
	s_cmpk_lg_u32 s10, 0x800
	s_cbranch_scc1 .Lnm_stride
	s_cmpk_gt_i32 s24, 0x7fff
	s_cbranch_scc1 .Lnm_stride
	s_add_i32 s99, s24, 1
	s_and_b32 s100, s99, 15
	s_cmp_lg_u32 s100, 0
	s_cbranch_scc1 .Lnm_set
	s_lshr_b32 s99, s24, 4
	s_add_i32 s99, s99, 0x8000
	s_branch .Lnm_set
.Lnm_stride:
	s_add_i32 s99, s24, s10
.Lnm_set:
	s_mov_b32 s24, s99
	s_sub_i32 s100, s24, s98
	s_lshl_b32 s100, s100, 11
	s_mov_b32 s101, 0
	s_waitcnt lgkmcnt(0)
	v_add_f32_e32 v0, v0, v38
	ds_bpermute_b32 v38, v49, v0
	s_cmp_lt_i32 s24, s20
	s_waitcnt lgkmcnt(0)
	v_add_f32_e32 v0, v0, v38
	ds_bpermute_b32 v38, v50, v0
	s_waitcnt lgkmcnt(0)
	v_add_f32_e32 v0, v0, v38
	ds_bpermute_b32 v38, v51, v0
	s_waitcnt lgkmcnt(0)
	v_add_f32_e32 v0, v0, v38
	ds_bpermute_b32 v38, v52, v0
	s_waitcnt lgkmcnt(0)
	v_add_f32_e32 v0, v0, v38
	v_fmamk_f32 v0, v0, 0x3a800000, v240
	v_cmp_gt_f32_e32 vcc, s77, v0
	v_mul_f32_e32 v38, 0x4f800000, v0
	s_nop 0
	v_cndmask_b32_e32 v0, v0, v38, vcc
	v_sqrt_f32_e32 v38, v0
	s_nop 0
	v_add_u32_e32 v39, -1, v38
	v_fma_f32 v40, -v39, v38, v0
	v_cmp_ge_f32_e64 s[2:3], 0, v40
	v_add_u32_e32 v40, 1, v38
	s_nop 0
	v_cndmask_b32_e64 v39, v38, v39, s[2:3]
	v_fma_f32 v38, -v40, v38, v0
	v_cmp_lt_f32_e64 s[2:3], 0, v38
	s_nop 1
	v_cndmask_b32_e64 v38, v39, v40, s[2:3]
	v_mul_f32_e32 v39, 0x37800000, v38
	v_cndmask_b32_e32 v38, v38, v39, vcc
	v_cmp_class_f32_e32 vcc, v0, v241
	s_nop 1
	v_cndmask_b32_e32 v0, v38, v0, vcc
	v_div_scale_f32 v38, s[2:3], v0, v0, 1.0
	v_rcp_f32_e32 v39, v38
	s_nop 0
	v_fma_f32 v40, -v38, v39, 1.0
	v_fmac_f32_e32 v39, v40, v39
	v_div_scale_f32 v40, vcc, 1.0, v0, 1.0
	v_mul_f32_e32 v41, v40, v39
	v_fma_f32 v42, -v38, v41, v40
	v_fmac_f32_e32 v41, v42, v39
	v_fma_f32 v38, -v38, v41, v40
	v_div_fmas_f32 v38, v38, v39, v41
	v_div_fixup_f32 v0, v38, v0, 1.0
	v_pk_mul_f32 v[32:33], v[32:33], v[0:1] op_sel_hi:[1,0]
	v_pk_mul_f32 v[30:31], v[30:31], v[0:1] op_sel_hi:[1,0]
	v_pk_mul_f32 v[32:33], v[4:5], v[32:33]
	v_pk_mul_f32 v[30:31], v[2:3], v[30:31]
	v_pk_mul_f32 v[28:29], v[28:29], v[0:1] op_sel_hi:[1,0]
	v_pk_mul_f32 v[26:27], v[26:27], v[0:1] op_sel_hi:[1,0]
	v_pk_mul_f32 v[28:29], v[8:9], v[28:29]
	v_pk_mul_f32 v[26:27], v[6:7], v[26:27]
	v_pk_mul_f32 v[24:25], v[24:25], v[0:1] op_sel_hi:[1,0]
	v_pk_mul_f32 v[22:23], v[22:23], v[0:1] op_sel_hi:[1,0]
	v_pk_mul_f32 v[24:25], v[12:13], v[24:25]
	v_pk_mul_f32 v[22:23], v[10:11], v[22:23]
	v_pk_mul_f32 v[20:21], v[20:21], v[0:1] op_sel_hi:[1,0]
	v_pk_mul_f32 v[18:19], v[18:19], v[0:1] op_sel_hi:[1,0]
	v_pk_mul_f32 v[20:21], v[16:17], v[20:21]
	v_pk_mul_f32 v[18:19], v[14:15], v[18:19]
	v_pk_add_f32 v[118:119], v[118:119], 1.0 op_sel_hi:[1,0]
	v_pk_add_f32 v[116:117], v[116:117], 1.0 op_sel_hi:[1,0]
	v_pk_add_f32 v[122:123], v[122:123], 1.0 op_sel_hi:[1,0]
	v_pk_add_f32 v[120:121], v[120:121], 1.0 op_sel_hi:[1,0]
	v_pk_fma_f32 v[32:33], v[118:119], v[32:33], v[102:103]
	v_pk_fma_f32 v[30:31], v[116:117], v[30:31], v[100:101]
	v_pk_add_f32 v[126:127], v[126:127], 1.0 op_sel_hi:[1,0]
	v_pk_add_f32 v[124:125], v[124:125], 1.0 op_sel_hi:[1,0]
	v_cvt_pk_bf16_f32 v30, v30, v31
	v_cvt_pk_bf16_f32 v31, v32, v33
	global_store_dwordx2 v[36:37], v[30:31], off
	v_pk_fma_f32 v[28:29], v[122:123], v[28:29], v[106:107]
	v_pk_fma_f32 v[26:27], v[120:121], v[26:27], v[104:105]
	v_pk_add_f32 v[130:131], v[130:131], 1.0 op_sel_hi:[1,0]
	v_pk_add_f32 v[128:129], v[128:129], 1.0 op_sel_hi:[1,0]
	v_cvt_pk_bf16_f32 v26, v26, v27
	v_cvt_pk_bf16_f32 v27, v28, v29
	global_store_dwordx2 v[36:37], v[26:27], off offset:512
	v_pk_fma_f32 v[24:25], v[126:127], v[24:25], v[110:111]
	v_pk_fma_f32 v[22:23], v[124:125], v[22:23], v[108:109]
	s_nop 0
	v_cvt_pk_bf16_f32 v22, v22, v23
	v_cvt_pk_bf16_f32 v23, v24, v25
	global_store_dwordx2 v[36:37], v[22:23], off offset:1024
	v_pk_fma_f32 v[20:21], v[130:131], v[20:21], v[114:115]
	v_pk_fma_f32 v[18:19], v[128:129], v[18:19], v[112:113]
	s_nop 0
	v_cvt_pk_bf16_f32 v18, v18, v19
	v_cvt_pk_bf16_f32 v19, v20, v21
	global_store_dwordx2 v[36:37], v[18:19], off offset:1536
	v_lshl_add_u64 v[36:37], v[36:37], 0, s[100:101]
	s_cbranch_scc0 .LBB0_784
